# hand-written weight conversion: LDS-DMA tile loads, 2 items in flight per wave, swizzled LDS transpose (replaces compiler conversion loop)
# speedup vs baseline: 1.0145x; 1.0031x over previous
; #pragma unroll
;     for (int i = 0; i < 32; ++i) { const int kk = 2 * i + (lane >> 5); const int k = k0 + kk, kr = perm ? ((k & ~511) | fnet_chan(k & 511)) : k;
;         scr[kk * 33 + (lane & 31)] = __builtin_nontemporal_load(W + (size_t)kr * N + n0 + (lane & 31)); }
;     LDS_WAIT(); asm volatile("" ::: "memory");
;     const int c = lane & 7;
; #pragma unroll
;     for (int j = 0; j < 4; ++j) { const int n = (lane >> 3) + 8 * j; const LAS float* s = scr + (8 * c) * 33 + n;
;         v4u o; o.x = pk2(s[0 * 33], s[1 * 33]); o.y = pk2(s[2 * 33], s[3 * 33]); o.z = pk2(s[4 * 33], s[5 * 33]); o.w = pk2(s[6 * 33], s[7 * 33]);
;         __builtin_nontemporal_store(o, (GAS v4u*)(WT + (size_t)(drow0 + n) * K + k0 + 8 * c)); }
;     LDS_WAIT(); asm volatile("" ::: "memory");
; }
; DI void phase_prologue(const Frame& F0, const Args& a) {
;     ...
;         for (int it = gw; it < NITEMS; it += NGW) {
;             int r = it;
;             if (r < 2 * I_IN) { const int j = r / I_IN; r %= I_IN; const int nblk = GIN / 32, kb = r / nblk, nb = r % nblk;
;                 transpose_item(a.gla_w_in + (size_t)j * DM * GIN, DM, GIN, (bf16*)(ws + WS_WIN) + (size_t)j * GIN_PAD * DM, 64 * kb, 32 * nb, 32 * nb, scr, F.lane); continue; }
;             r -= 2 * I_IN;
;             if (r < 2 * I_SQ) { const int j = r / I_SQ; r %= I_SQ; const int kb = r / 64, nb = r % 64;
;                 transpose_item(a.gla_w_out + (size_t)j * DM * DM, DM, DM, (bf16*)(ws + WS_WGO) + (size_t)j * DM * DM, 64 * kb, 32 * nb, 32 * nb, scr, F.lane); continue; }
;             r -= 2 * I_SQ;
;             if (r < 2 * I_SQ) { const int j = r / I_SQ; r %= I_SQ; const int kb = r / 64, nb = r % 64;
;                 transpose_item(a.fnet_w_out + (size_t)j * DM * DM, DM, DM, (bf16*)(ws + WS_WFO) + (size_t)j * DM * DM, 64 * kb, 32 * nb, 32 * nb, scr, F.lane, 1); continue; }
;             r -= 2 * I_SQ;
;             if (r < DEPTH * I_GU) { const int j = r / I_GU; r %= I_GU; const int nblk = 2 * DFF / 32, kb = r / nblk, nb = r % nblk, n0 = 32 * nb;
;                 const int jj = n0 < DFF ? n0 : n0 - DFF; const int drow = (jj >> 7) * 256 + (n0 < DFF ? 0 : 128) + (jj & 127);
;                 transpose_item(a.ffn_w_gu + (size_t)j * DM * 2 * DFF, DM, 2 * DFF, (bf16*)(ws + WS_WGU) + (size_t)j * 2 * DFF * DM, 64 * kb, n0, drow, scr, F.lane); continue; }
;             r -= DEPTH * I_GU;
.Lconv_entry:
	s_mov_b64 s[62:63], s[86:87]
	s_lshl_b32 s20, s44, 14
	v_mov_b32_e32 v1, v78
	v_and_b32_e32 v2, 7, v1
	v_lshrrev_b32_e32 v3, 3, v1
	v_lshlrev_b32_e32 v4, 4, v2
	s_mov_b32 s12, 0xfffffe00
	v_mov_b32_e32 v12, v3
	v_lshrrev_b32_e32 v5, 2, v12
	v_xor_b32_e32 v5, v5, v2
	v_lshlrev_b32_e32 v5, 4, v5
	v_and_b32_e32 v6, 3, v3
	v_lshl_add_u32 v5, v6, 2, v5
	v_lshl_add_u32 v8, v2, 10, v5
	v_add_u32_e32 v13, 8, v3
	v_lshrrev_b32_e32 v5, 2, v13
	v_xor_b32_e32 v5, v5, v2
	v_lshlrev_b32_e32 v5, 4, v5
	v_and_b32_e32 v6, 3, v3
	v_lshl_add_u32 v5, v6, 2, v5
	v_lshl_add_u32 v9, v2, 10, v5
	v_add_u32_e32 v14, 16, v3
	v_lshrrev_b32_e32 v5, 2, v14
	v_xor_b32_e32 v5, v5, v2
	v_lshlrev_b32_e32 v5, 4, v5
	v_and_b32_e32 v6, 3, v3
	v_lshl_add_u32 v5, v6, 2, v5
	v_lshl_add_u32 v10, v2, 10, v5
	v_add_u32_e32 v15, 24, v3
	v_lshrrev_b32_e32 v5, 2, v15
	v_xor_b32_e32 v5, v5, v2
	v_lshlrev_b32_e32 v5, 4, v5
	v_and_b32_e32 v6, 3, v3
	v_lshl_add_u32 v5, v6, 2, v5
	v_lshl_add_u32 v11, v2, 10, v5
	v_mov_b32_e32 v82, v4
	v_xor_b32_e32 v83, 0x10, v4
	v_xor_b32_e32 v84, 0x20, v4
	v_xor_b32_e32 v85, 0x30, v4
	v_xor_b32_e32 v86, 0x40, v4
	v_xor_b32_e32 v87, 0x50, v4
	v_xor_b32_e32 v88, 0x60, v4
	v_xor_b32_e32 v89, 0x70, v4
	s_mov_b32 s19, 0
	s_mov_b32 s21, 0
	s_mov_b32 s22, 0
	s_mov_b32 s94, s90
.Lcv_top:
	s_cmp_eq_u32 s92, 1
	s_cbranch_scc1 .Lcv_map1
	s_cmp_eq_u32 s92, 2
	s_cbranch_scc1 .Lcv_map2
	s_cmp_eq_u32 s92, 3
	s_cbranch_scc1 .Lcv_map3
	s_mov_b32 s6, s94
	s_branch .Lcv_mapped
.Lcv_map1:
	s_mov_b32 s0, 0xb420
	s_cmp_lt_i32 s94, 0x4c20
	s_cselect_b32 s0, 0x3020, s0
	s_cmp_lt_i32 s94, 0x2020
	s_cselect_b32 s0, 0x1820, s0
	s_cmp_lt_i32 s94, 0x1820
	s_cselect_b32 s0, 0x0, s0
	s_add_i32 s6, s94, s0
	s_branch .Lcv_mapped
.Lcv_map2:
	s_mov_b32 s0, 0xb130
	s_cmp_lt_i32 s94, 0x6510
	s_cselect_b32 s0, 0x5420, s0
	s_cmp_lt_i32 s94, 0x2820
	s_cselect_b32 s0, 0x2020, s0
	s_cmp_lt_i32 s94, 0x1820
	s_cselect_b32 s0, 0x1820, s0
	s_add_i32 s6, s94, s0
	s_branch .Lcv_mapped
.Lcv_map3:
	s_mov_b32 s0, 0xdd30
	s_cmp_lt_i32 s94, 0x4f10
	s_cselect_b32 s0, 0xb130, s0
	s_cmp_lt_i32 s94, 0x800
	s_cselect_b32 s0, 0x4840, s0
	s_add_i32 s6, s94, s0
	s_branch .Lcv_mapped
.Lcv_mapped:
	s_cmp_lt_u32 s6, 0x3040
	s_cbranch_scc1 .Lcv_t_win
	s_cmp_lt_u32 s6, 0x4040
	s_cbranch_scc1 .Lcv_t_go
	s_cmp_lt_u32 s6, 0x5040
	s_cbranch_scc1 .Lcv_t_fo
	s_cmp_lt_u32 s6, 0x10040
	s_cbranch_scc1 .Lcv_t_gu
.Lcv_t_dn:
	s_sub_u32 s0, s6, 0x10040
	s_mul_hi_u32 s7, s0, 0xba2e9
	s_mul_i32 s1, s7, 0x1600
	s_sub_u32 s0, s0, s1
	s_lshr_b32 s8, s0, 6
	s_mul_i32 s1, s8, 0x40
	s_sub_u32 s9, s0, s1
	s_mov_b32 s10, 0x1600
	s_mov_b32 s16, 0x2000
	s_mov_b32 s11, 0x800
	s_mov_b32 s30, 0x2c00
	s_mov_b32 s17, 0
	s_mov_b32 s14, 0x102a0000
	s_lshl_b32 s15, s9, 5
	v_readlane_b32 s4, v252, 0
	v_readlane_b32 s5, v252, 1
	s_branch .Lcv_tcommon
.Lcv_t_gu:
	s_sub_u32 s0, s6, 0x5040
	s_mul_hi_u32 s7, s0, 0x5d175
	s_mul_i32 s1, s7, 0x2c00
	s_sub_u32 s0, s0, s1
	s_mul_hi_u32 s8, s0, 0xba2e8c
	s_mul_i32 s1, s8, 0x160
	s_sub_u32 s9, s0, s1
	s_mov_b32 s10, 0x800
	s_mov_b32 s16, 0xb000
	s_mov_b32 s11, 0x2c00
	s_mov_b32 s30, 0x1000
	s_mov_b32 s17, 0
	s_mov_b32 s14, 0x52a0000
	s_lshl_b32 s15, s9, 5
	s_cmp_lt_u32 s15, 0x1600
	s_cselect_b32 s0, 0, 0x1600
	s_cselect_b32 s1, 0, 0x80
	s_sub_u32 s15, s15, s0
	s_lshr_b32 s0, s15, 7
	s_lshl_b32 s0, s0, 8
	s_and_b32 s15, s15, 0x7f
	s_add_u32 s15, s15, s0
	s_add_u32 s15, s15, s1
	v_readlane_b32 s4, v252, 38
	v_readlane_b32 s5, v252, 39
	s_branch .Lcv_tcommon
.Lcv_t_fo:
	s_sub_u32 s0, s6, 0x4040
	s_lshr_b32 s7, s0, 11
	s_mul_i32 s1, s7, 0x800
	s_sub_u32 s0, s0, s1
	s_lshr_b32 s8, s0, 6
	s_mul_i32 s1, s8, 0x40
	s_sub_u32 s9, s0, s1
	s_mov_b32 s10, 0x800
	s_mov_b32 s16, 0x2000
	s_mov_b32 s11, 0x800
	s_mov_b32 s30, 0x1000
	s_mov_b32 s17, 1
	s_mov_b32 s14, 0x42a0000
	s_lshl_b32 s15, s9, 5
	v_readlane_b32 s4, v252, 36
	v_readlane_b32 s5, v252, 37
	s_branch .Lcv_tcommon
.Lcv_t_go:
	s_sub_u32 s0, s6, 0x3040
	s_lshr_b32 s7, s0, 11
	s_mul_i32 s1, s7, 0x800
	s_sub_u32 s0, s0, s1
	s_lshr_b32 s8, s0, 6
	s_mul_i32 s1, s8, 0x40
	s_sub_u32 s9, s0, s1
	s_mov_b32 s10, 0x800
	s_mov_b32 s16, 0x2000
	s_mov_b32 s11, 0x800
	s_mov_b32 s30, 0x1000
	s_mov_b32 s17, 0
	s_mov_b32 s14, 0x32a0000
	s_lshl_b32 s15, s9, 5
	v_readlane_b32 s4, v252, 34
	v_readlane_b32 s5, v252, 35
	s_branch .Lcv_tcommon
.Lcv_t_win:
	s_mov_b32 s0, s6
	s_mul_hi_u32 s7, s0, 0xa9c85
	s_mul_i32 s1, s7, 0x1820
	s_sub_u32 s0, s0, s1
	s_mul_hi_u32 s8, s0, 0x1539095
	s_mul_i32 s1, s8, 0xc1
	s_sub_u32 s9, s0, s1
	s_mov_b32 s10, 0x800
	s_mov_b32 s16, 0x6080
	s_mov_b32 s11, 0x1900
	s_mov_b32 s30, 0x1000
	s_mov_b32 s17, 0
	s_mov_b32 s14, 0xa0000
	s_lshl_b32 s15, s9, 5
	v_readlane_b32 s4, v252, 22
	v_readlane_b32 s5, v252, 23
	s_branch .Lcv_tcommon
.Lcv_tcommon:
	s_lshl_b32 s18, s8, 6
	s_mul_i32 s0, s7, s10
	s_mul_i32 s0, s0, s16
	s_lshl_b32 s1, s9, 7
	s_add_u32 s0, s0, s1
	s_nop 2
	s_add_u32 s4, s4, s0
	s_addc_u32 s5, s5, 0
	s_mul_i32 s0, s7, s11
	s_add_u32 s0, s0, s15
	s_mul_i32 s0, s0, s30
	s_lshl_b32 s1, s18, 1
	s_add_u32 s0, s0, s1
	s_add_u32 s0, s0, s14
	s_add_u32 s28, s62, s0
	s_addc_u32 s29, s63, 0
	v_add_u32_e32 v7, s18, v3
	s_add_i32 s23, s20, s22
	s_cmp_eq_u32 s17, 0
	s_cbranch_scc0 .Lcv_issue_perm
	v_mov_b32_e32 v6, v7
	v_mad_u32_u24 v6, v6, s16, v82
	s_mov_b32 m0, s23
	s_nop 0
	global_load_lds_dwordx4 v6, s[4:5] nt
	v_add_u32_e32 v6, 8, v7
	v_mad_u32_u24 v6, v6, s16, v83
	s_add_u32 m0, s23, 0x400
	s_nop 0
	global_load_lds_dwordx4 v6, s[4:5] nt
	v_add_u32_e32 v6, 16, v7
	v_mad_u32_u24 v6, v6, s16, v84
	s_add_u32 m0, s23, 0x800
	s_nop 0
	global_load_lds_dwordx4 v6, s[4:5] nt
	v_add_u32_e32 v6, 24, v7
	v_mad_u32_u24 v6, v6, s16, v85
	s_add_u32 m0, s23, 0xc00
	s_nop 0
	global_load_lds_dwordx4 v6, s[4:5] nt
	v_add_u32_e32 v6, 32, v7
	v_mad_u32_u24 v6, v6, s16, v86
	s_add_u32 m0, s23, 0x1000
	s_nop 0
	global_load_lds_dwordx4 v6, s[4:5] nt
	v_add_u32_e32 v6, 40, v7
	v_mad_u32_u24 v6, v6, s16, v87
	s_add_u32 m0, s23, 0x1400
	s_nop 0
	global_load_lds_dwordx4 v6, s[4:5] nt
	v_add_u32_e32 v6, 48, v7
	v_mad_u32_u24 v6, v6, s16, v88
	s_add_u32 m0, s23, 0x1800
	s_nop 0
	global_load_lds_dwordx4 v6, s[4:5] nt
	v_add_u32_e32 v6, 56, v7
	v_mad_u32_u24 v6, v6, s16, v89
	s_add_u32 m0, s23, 0x1c00
	s_nop 0
	global_load_lds_dwordx4 v6, s[4:5] nt
	s_branch .Lcv_issued
; #define GAS __attribute__((address_space(1)))
; #define LAS __attribute__((address_space(3)))
; #define LDS_WAIT() asm volatile("s_waitcnt lgkmcnt(0)" ::: "memory")
; DI unsigned pk2(float lo, float hi) { f32x2_t v = {lo, hi}; bf16x2_t b = __builtin_convertvector(v, bf16x2_t); return __builtin_bit_cast(unsigned, b); }
;     ...
;     for (int i = 0; i < 32; ++i) { const int kk = 2 * i + (lane >> 5); const int k = k0 + kk, kr = perm ? ((k & ~511) | fnet_chan(k & 511)) : k;
;         scr[kk * 33 + (lane & 31)] = __builtin_nontemporal_load(W + (size_t)kr * N + n0 + (lane & 31)); }
;     LDS_WAIT(); asm volatile("" ::: "memory");
;     const int c = lane & 7;
; #pragma unroll
;     for (int j = 0; j < 4; ++j) { const int n = (lane >> 3) + 8 * j; const LAS float* s = scr + (8 * c) * 33 + n;
;         v4u o; o.x = pk2(s[0 * 33], s[1 * 33]); o.y = pk2(s[2 * 33], s[3 * 33]); o.z = pk2(s[4 * 33], s[5 * 33]); o.w = pk2(s[6 * 33], s[7 * 33]);
;         __builtin_nontemporal_store(o, (GAS v4u*)(WT + (size_t)(drow0 + n) * K + k0 + 8 * c)); }
;     LDS_WAIT(); asm volatile("" ::: "memory");
.Lcv_issue_perm:
	v_mov_b32_e32 v6, v7
	v_and_b32_e32 v90, 0x1ff, v6
	v_sub_u32_e32 v91, 0x300, v90
	v_cmp_lt_u32_e32 vcc, 0x100, v90
	s_nop 1
	v_cndmask_b32_e32 v90, v90, v91, vcc
	v_and_or_b32 v6, v6, s12, v90
	v_mad_u32_u24 v6, v6, s16, v82
	s_mov_b32 m0, s23
	s_nop 0
	global_load_lds_dwordx4 v6, s[4:5] nt
	v_add_u32_e32 v6, 8, v7
	v_and_b32_e32 v90, 0x1ff, v6
	v_sub_u32_e32 v91, 0x300, v90
	v_cmp_lt_u32_e32 vcc, 0x100, v90
	s_nop 1
	v_cndmask_b32_e32 v90, v90, v91, vcc
	v_and_or_b32 v6, v6, s12, v90
	v_mad_u32_u24 v6, v6, s16, v83
	s_add_u32 m0, s23, 0x400
	s_nop 0
	global_load_lds_dwordx4 v6, s[4:5] nt
	v_add_u32_e32 v6, 16, v7
	v_and_b32_e32 v90, 0x1ff, v6
	v_sub_u32_e32 v91, 0x300, v90
	v_cmp_lt_u32_e32 vcc, 0x100, v90
	s_nop 1
	v_cndmask_b32_e32 v90, v90, v91, vcc
	v_and_or_b32 v6, v6, s12, v90
	v_mad_u32_u24 v6, v6, s16, v84
	s_add_u32 m0, s23, 0x800
	s_nop 0
	global_load_lds_dwordx4 v6, s[4:5] nt
	v_add_u32_e32 v6, 24, v7
	v_and_b32_e32 v90, 0x1ff, v6
	v_sub_u32_e32 v91, 0x300, v90
	v_cmp_lt_u32_e32 vcc, 0x100, v90
	s_nop 1
	v_cndmask_b32_e32 v90, v90, v91, vcc
	v_and_or_b32 v6, v6, s12, v90
	v_mad_u32_u24 v6, v6, s16, v85
	s_add_u32 m0, s23, 0xc00
	s_nop 0
	global_load_lds_dwordx4 v6, s[4:5] nt
	v_add_u32_e32 v6, 32, v7
	v_and_b32_e32 v90, 0x1ff, v6
	v_sub_u32_e32 v91, 0x300, v90
	v_cmp_lt_u32_e32 vcc, 0x100, v90
	s_nop 1
	v_cndmask_b32_e32 v90, v90, v91, vcc
	v_and_or_b32 v6, v6, s12, v90
	v_mad_u32_u24 v6, v6, s16, v86
	s_add_u32 m0, s23, 0x1000
	s_nop 0
	global_load_lds_dwordx4 v6, s[4:5] nt
	v_add_u32_e32 v6, 40, v7
	v_and_b32_e32 v90, 0x1ff, v6
	v_sub_u32_e32 v91, 0x300, v90
	v_cmp_lt_u32_e32 vcc, 0x100, v90
	s_nop 1
	v_cndmask_b32_e32 v90, v90, v91, vcc
	v_and_or_b32 v6, v6, s12, v90
	v_mad_u32_u24 v6, v6, s16, v87
	s_add_u32 m0, s23, 0x1400
	s_nop 0
	global_load_lds_dwordx4 v6, s[4:5] nt
	v_add_u32_e32 v6, 48, v7
	v_and_b32_e32 v90, 0x1ff, v6
	v_sub_u32_e32 v91, 0x300, v90
	v_cmp_lt_u32_e32 vcc, 0x100, v90
	s_nop 1
	v_cndmask_b32_e32 v90, v90, v91, vcc
	v_and_or_b32 v6, v6, s12, v90
	v_mad_u32_u24 v6, v6, s16, v88
	s_add_u32 m0, s23, 0x1800
	s_nop 0
	global_load_lds_dwordx4 v6, s[4:5] nt
	v_add_u32_e32 v6, 56, v7
	v_and_b32_e32 v90, 0x1ff, v6
	v_sub_u32_e32 v91, 0x300, v90
	v_cmp_lt_u32_e32 vcc, 0x100, v90
	s_nop 1
	v_cndmask_b32_e32 v90, v90, v91, vcc
	v_and_or_b32 v6, v6, s12, v90
	v_mad_u32_u24 v6, v6, s16, v89
	s_add_u32 m0, s23, 0x1c00
	s_nop 0
	global_load_lds_dwordx4 v6, s[4:5] nt
.Lcv_issued:
	s_cmp_eq_u32 s19, 0
	s_cbranch_scc1 .Lcv_promote
	s_waitcnt vmcnt(8)
.Lcv_process:
	s_add_i32 s0, s20, s21
	v_add_u32_e32 v16, s0, v8
	v_add_u32_e32 v17, s0, v9
	v_add_u32_e32 v18, s0, v10
	v_add_u32_e32 v19, s0, v11
	ds_read2_b32 v[20:21], v16 offset1:32
	ds_read2_b32 v[22:23], v16 offset0:64 offset1:96
	ds_read2_b32 v[24:25], v16 offset0:128 offset1:160
	ds_read2_b32 v[26:27], v16 offset0:192 offset1:224
	ds_read2_b32 v[28:29], v17 offset1:32
	ds_read2_b32 v[30:31], v17 offset0:64 offset1:96
	ds_read2_b32 v[32:33], v17 offset0:128 offset1:160
	ds_read2_b32 v[34:35], v17 offset0:192 offset1:224
	ds_read2_b32 v[36:37], v18 offset1:32
	ds_read2_b32 v[38:39], v18 offset0:64 offset1:96
	ds_read2_b32 v[40:41], v18 offset0:128 offset1:160
	ds_read2_b32 v[42:43], v18 offset0:192 offset1:224
	ds_read2_b32 v[44:45], v19 offset1:32
	ds_read2_b32 v[46:47], v19 offset0:64 offset1:96
	ds_read2_b32 v[48:49], v19 offset0:128 offset1:160
	ds_read2_b32 v[50:51], v19 offset0:192 offset1:224
	s_waitcnt lgkmcnt(12)
	v_cvt_pk_bf16_f32 v56, v20, v21
	v_cvt_pk_bf16_f32 v57, v22, v23
	v_cvt_pk_bf16_f32 v58, v24, v25
	v_cvt_pk_bf16_f32 v59, v26, v27
	v_mad_u32_u24 v78, v12, s26, v4
	global_store_dwordx4 v78, v[56:59], s[24:25] nt
	s_waitcnt lgkmcnt(8)
	v_cvt_pk_bf16_f32 v60, v28, v29
	v_cvt_pk_bf16_f32 v61, v30, v31
	v_cvt_pk_bf16_f32 v62, v32, v33
	v_cvt_pk_bf16_f32 v63, v34, v35
	v_mad_u32_u24 v79, v13, s26, v4
	global_store_dwordx4 v79, v[60:63], s[24:25] nt
	s_waitcnt lgkmcnt(4)
	v_cvt_pk_bf16_f32 v64, v36, v37
	v_cvt_pk_bf16_f32 v65, v38, v39
	v_cvt_pk_bf16_f32 v66, v40, v41
	v_cvt_pk_bf16_f32 v67, v42, v43
	v_mad_u32_u24 v80, v14, s26, v4
	global_store_dwordx4 v80, v[64:67], s[24:25] nt
	s_waitcnt lgkmcnt(0)
	v_cvt_pk_bf16_f32 v68, v44, v45
	v_cvt_pk_bf16_f32 v69, v46, v47
	v_cvt_pk_bf16_f32 v70, v48, v49
	v_cvt_pk_bf16_f32 v71, v50, v51
	v_mad_u32_u24 v81, v15, s26, v4
	global_store_dwordx4 v81, v[68:71], s[24:25] nt
	s_cmp_eq_u32 s19, 2
	s_cbranch_scc1 .Lconv_exit
.Lcv_promote:
	s_mov_b64 s[24:25], s[28:29]
	s_mov_b32 s26, s30
	s_mov_b32 s21, s22
	s_mov_b32 s19, 1
	s_mov_b32 s90, s94
	s_add_i32 s94, s90, s93
	s_xor_b32 s22, s21, 0x2000
	s_cmp_lt_i32 s94, s91
	s_cbranch_scc1 .Lcv_top
	s_mov_b32 s19, 2
	s_waitcnt vmcnt(0)
	s_branch .Lcv_process

; DI void phase_prologue(const Frame& F0, const Args& a) {
;     ...
;         for (int it = gw; it < NITEMS; it += NGW) {
;             int r = it;
; DI void phase_scan(const Frame& F0, const Args& a, int colmajor) {
;     ...
;     for (int it = F.vcu; it < 256; it += F.G) {
;         if ((it & 31) >= 16) continue;
.Lconv_scan_idle:
	s_cmp_eq_u32 s3, 0x100
	s_cbranch_scc0 .LBB0_821
	v_writelane_b32 v100, s11, 0
	v_writelane_b32 v100, s20, 1
	v_writelane_b32 v100, s21, 2
	v_writelane_b32 v100, s22, 3
	v_writelane_b32 v100, s26, 4
	v_writelane_b32 v100, s28, 5
	v_writelane_b32 v100, s29, 6
	v_writelane_b32 v100, s30, 7
	v_writelane_b32 v100, s44, 8
	v_writelane_b32 v100, s86, 9
	v_writelane_b32 v100, s87, 10
	v_mov_b32_e32 v101, v1
	v_mov_b32_e32 v102, v3
	v_readlane_b32 s0, v255, 17
	v_readlane_b32 s1, v252, 48
	v_readlane_b32 s44, v252, 49
	v_readlane_b32 s86, v252, 46
	v_readlane_b32 s87, v252, 47
	v_mov_b32_e32 v78, v222
	s_lshr_b32 s4, s1, 5
	s_lshl_b32 s4, s4, 4
	s_and_b32 s5, s1, 15
	s_or_b32 s4, s4, s5
	s_lshl_b32 s4, s4, 3
	s_add_i32 s90, s4, s44
	s_movk_i32 s93, 0x400
	s_mov_b32 s4, 0x7b10
	s_mov_b32 s5, 0x7b10
	s_cmp_eq_u32 s0, 0
	s_cselect_b32 s92, 2, 3
	s_cselect_b32 s91, s4, s5
	s_cmp_lt_i32 s90, s91
	s_cbranch_scc1 .Lconv_entry
.Lconv_ret_scan:
	s_waitcnt vmcnt(0) lgkmcnt(0)
	v_readlane_b32 s11, v100, 0
	v_readlane_b32 s20, v100, 1
	v_readlane_b32 s21, v100, 2
	v_readlane_b32 s22, v100, 3
	v_readlane_b32 s26, v100, 4
	v_readlane_b32 s28, v100, 5
	v_readlane_b32 s29, v100, 6
	v_readlane_b32 s30, v100, 7
	v_readlane_b32 s44, v100, 8
	v_readlane_b32 s86, v100, 9
	v_readlane_b32 s87, v100, 10
	v_mov_b32_e32 v1, v101
	v_mov_b32_e32 v3, v102
	s_nop 4
	s_branch .LBB0_821
